# baseline (speedup 1.0000x reference)
; __device__ __forceinline__ float bflo(unsigned u) { return __uint_as_float(u << 16); }
; __device__ __forceinline__ float bfhi(unsigned u) { return __uint_as_float(u & 0xffff0000u); }
; __device__ __forceinline__ void phase_peer_u(const Params& p, int layer, int xs, int wid0, int wstride, char* smraw) {
;     ...
;       const float x0 = bflo(xv[0]), x1 = bfhi(xv[0]), x2 = bflo(xv[1]), x3 = bfhi(xv[1]);
;       float mx = fmaxf(fmaxf(fabsf(x0), fabsf(x1)), fmaxf(fabsf(x2), fabsf(x3)));
; #pragma unroll
;       for (int m = 32; m >= 1; m >>= 1) mx = fmaxf(mx, __shfl_xor(mx, m));
;       const float inv = mx > 0.f ? 127.f / mx : 0.f;
;       sx = mx * (1.f / 127.f);
;       const int q0 = __float2int_rn(x0 * inv), q1 = __float2int_rn(x1 * inv), q2 = __float2int_rn(x2 * inv), q3 = __float2int_rn(x3 * inv);
;       asm volatile("" ::: "memory");
;       *(int*)(xqs + l * 4) = (q0 & 0xff) | ((q1 & 0xff) << 8) | ((q2 & 0xff) << 16) | ((q3 & 0xff) << 24);
;       asm volatile("" ::: "memory");
;       __builtin_amdgcn_wave_barrier();
;       asm volatile("" ::: "memory");
;       const u32x4 xa = *(const u32x4*)(xqs + j * 32), xb = *(const u32x4*)(xqs + j * 32 + 16);
;       asm volatile("" ::: "memory");
; #pragma unroll
;       for (int m = 0; m < 4; ++m) { xq[m] = (int)xa[m]; xq[4 + m] = (int)xb[m]; }
; #pragma unroll
;       for (int m = 0; m < 8; ++m) sumx = __builtin_amdgcn_sdot4(xq[m], 0x01010101, sumx, false);
;     }
;     const int corr = 8 * sumx;
;     float pr[16];
; #pragma unroll
;     for (int i = 0; i < 16; ++i) {
;       int a = 0;
; #pragma unroll
;       for (int m = 0; m < 4; ++m) {
;         const unsigned dw = q[i][m];
;         a = __builtin_amdgcn_sdot4((int)(dw & 0x0f0f0f0fu), xq[2 * m], a, false);
;         a = __builtin_amdgcn_sdot4((int)((dw >> 4) & 0x0f0f0f0fu), xq[2 * m + 1], a, false);
;       }
;       a -= corr;
.Lmy_pu0_noissueA:
	v_lshlrev_b32_e32 v40, 16, v26
	v_and_b32_e32 v41, 0xffff0000, v26
	v_lshlrev_b32_e32 v42, 16, v27
	v_and_b32_e32 v43, 0xffff0000, v27
	v_max_f32_e64 v44, |v40|, |v41|
	v_max3_f32 v44, |v42|, |v43|, v44
	s_nop 1
	v_max_f32_dpp v44, v44, v44 quad_perm:[1,0,3,2] row_mask:0xf bank_mask:0xf bound_ctrl:1
	s_nop 1
	v_max_f32_dpp v44, v44, v44 quad_perm:[2,3,0,1] row_mask:0xf bank_mask:0xf bound_ctrl:1
	s_nop 1
	v_max_f32_dpp v44, v44, v44 row_half_mirror row_mask:0xf bank_mask:0xf bound_ctrl:1
	s_nop 1
	v_max_f32_dpp v44, v44, v44 row_mirror row_mask:0xf bank_mask:0xf bound_ctrl:1
	s_nop 0
	v_readlane_b32 s6, v44, 0
	v_readlane_b32 s7, v44, 16
	v_readlane_b32 s10, v44, 32
	v_readlane_b32 s11, v44, 48
	s_nop 1
	v_mov_b32_e32 v45, s6
	v_max_f32_e32 v45, s7, v45
	v_max_f32_e32 v45, s10, v45
	v_max_f32_e32 v45, s11, v45
	v_div_scale_f32 v46, s[18:19], v45, v45, s69
	v_rcp_f32_e32 v47, v46
	s_nop 0
	v_fma_f32 v48, -v46, v47, 1.0
	v_fmac_f32_e32 v47, v48, v47
	v_div_scale_f32 v48, vcc, s69, v45, s69
	v_mul_f32_e32 v49, v48, v47
	v_fma_f32 v50, -v46, v49, v48
	v_fmac_f32_e32 v49, v50, v47
	v_fma_f32 v46, -v46, v49, v48
	v_div_fmas_f32 v46, v46, v47, v49
	v_div_fixup_f32 v46, v46, v45, s69
	v_cmp_lt_f32_e32 vcc, 0, v45
	v_mul_f32_e32 v52, 0x3c010204, v45
	v_mov_b32_e32 v84, 0
	v_cndmask_b32_e32 v46, 0, v46, vcc
	v_mul_f32_e32 v40, v46, v40
	v_mul_f32_e32 v41, v46, v41
	v_mul_f32_e32 v42, v46, v42
	v_mul_f32_e32 v43, v46, v43
	v_rndne_f32_e32 v40, v40
	v_rndne_f32_e32 v41, v41
	v_rndne_f32_e32 v42, v42
	v_rndne_f32_e32 v43, v43
	v_cvt_i32_f32_e32 v40, v40
	v_cvt_i32_f32_e32 v41, v41
	v_cvt_i32_f32_e32 v42, v42
	v_cvt_i32_f32_e32 v43, v43
	v_and_b32_e32 v40, 0xff, v40
	v_and_b32_e32 v41, 0xff, v41
	v_and_b32_e32 v42, 0xff, v42
	v_lshl_or_b32 v40, v41, 8, v40
	v_lshl_or_b32 v40, v42, 16, v40
	v_lshl_or_b32 v40, v43, 24, v40
	ds_write_b32 v3, v40
	ds_read_b128 v[32:35], v4
	ds_read_b128 v[36:39], v4 offset:16
	s_waitcnt lgkmcnt(0)
	v_dot4c_i32_i8_e32 v84, 0x1010101, v32
	v_dot4c_i32_i8_e32 v84, 0x1010101, v34
	v_dot4c_i32_i8_e32 v84, 0x1010101, v36
	v_dot4c_i32_i8_e32 v84, 0x1010101, v38
	v_and_b32_e32 v56, s21, v106
	v_and_b32_e32 v57, s23, v106
	v_and_b32_e32 v58, s21, v110
	v_and_b32_e32 v59, s23, v110
	v_and_b32_e32 v60, s21, v114
	v_and_b32_e32 v61, s23, v114
	v_and_b32_e32 v62, s21, v118
	v_and_b32_e32 v63, s23, v118
	v_mul_i32_i24_e32 v85, -8, v84
	v_dot4_i32_i8 v64, v56, v32, v85
	v_dot4_i32_i8 v86, v57, v33, 0
	v_dot4_i32_i8 v65, v58, v32, v85
	v_dot4_i32_i8 v87, v59, v33, 0
	v_dot4_i32_i8 v66, v60, v32, v85
	v_dot4_i32_i8 v88, v61, v33, 0
	v_dot4_i32_i8 v67, v62, v32, v85
	v_dot4_i32_i8 v89, v63, v33, 0
	v_and_b32_e32 v56, s21, v107
	v_and_b32_e32 v57, s23, v107
	v_and_b32_e32 v58, s21, v111
	v_and_b32_e32 v59, s23, v111
	v_and_b32_e32 v60, s21, v115
	v_and_b32_e32 v61, s23, v115
	v_and_b32_e32 v62, s21, v119
	v_and_b32_e32 v63, s23, v119
	v_dot4c_i32_i8_e32 v64, v56, v34
	v_dot4c_i32_i8_e32 v86, v57, v35
	v_dot4c_i32_i8_e32 v65, v58, v34
	v_dot4c_i32_i8_e32 v87, v59, v35
	v_dot4c_i32_i8_e32 v66, v60, v34
	v_dot4c_i32_i8_e32 v88, v61, v35
	v_dot4c_i32_i8_e32 v67, v62, v34
	v_dot4c_i32_i8_e32 v89, v63, v35
	v_and_b32_e32 v56, s21, v108
	v_and_b32_e32 v57, s23, v108
	v_and_b32_e32 v58, s21, v112
	v_and_b32_e32 v59, s23, v112
	v_and_b32_e32 v60, s21, v116
	v_and_b32_e32 v61, s23, v116
	v_and_b32_e32 v62, s21, v120
	v_and_b32_e32 v63, s23, v120
	v_dot4c_i32_i8_e32 v64, v56, v36
	v_dot4c_i32_i8_e32 v86, v57, v37
	v_dot4c_i32_i8_e32 v65, v58, v36
	v_dot4c_i32_i8_e32 v87, v59, v37
	v_dot4c_i32_i8_e32 v66, v60, v36
	v_dot4c_i32_i8_e32 v88, v61, v37
	v_dot4c_i32_i8_e32 v67, v62, v36
	v_dot4c_i32_i8_e32 v89, v63, v37
	v_and_b32_e32 v56, s21, v109
	v_and_b32_e32 v57, s23, v109
	v_and_b32_e32 v58, s21, v113
	v_and_b32_e32 v59, s23, v113
	v_and_b32_e32 v60, s21, v117
	v_and_b32_e32 v61, s23, v117
	v_and_b32_e32 v62, s21, v121
	v_and_b32_e32 v63, s23, v121
	v_dot4c_i32_i8_e32 v64, v56, v38
	v_dot4c_i32_i8_e32 v86, v57, v39
	v_dot4c_i32_i8_e32 v65, v58, v38
	v_dot4c_i32_i8_e32 v87, v59, v39
	v_dot4c_i32_i8_e32 v66, v60, v38
	v_dot4c_i32_i8_e32 v88, v61, v39
	v_dot4c_i32_i8_e32 v67, v62, v38
	v_dot4c_i32_i8_e32 v89, v63, v39
	s_nop 0
	v_lshl_add_u32 v68, v64, 4, v86
	v_lshl_add_u32 v69, v65, 4, v87
	v_lshl_add_u32 v70, v66, 4, v88
	v_lshl_add_u32 v71, v67, 4, v89
	v_and_b32_e32 v56, s21, v122
	v_and_b32_e32 v57, s23, v122
	v_and_b32_e32 v58, s21, v126
	v_and_b32_e32 v59, s23, v126
	v_and_b32_e32 v60, s21, v130
	v_and_b32_e32 v61, s23, v130
	v_and_b32_e32 v62, s21, v134
	v_and_b32_e32 v63, s23, v134
	v_dot4_i32_i8 v64, v56, v32, v85
	v_dot4_i32_i8 v86, v57, v33, 0
	v_dot4_i32_i8 v65, v58, v32, v85
	v_dot4_i32_i8 v87, v59, v33, 0
	v_dot4_i32_i8 v66, v60, v32, v85
	v_dot4_i32_i8 v88, v61, v33, 0
	v_dot4_i32_i8 v67, v62, v32, v85
	v_dot4_i32_i8 v89, v63, v33, 0
	v_and_b32_e32 v56, s21, v123
	v_and_b32_e32 v57, s23, v123
	v_and_b32_e32 v58, s21, v127
	v_and_b32_e32 v59, s23, v127
	v_and_b32_e32 v60, s21, v131
	v_and_b32_e32 v61, s23, v131
	v_and_b32_e32 v62, s21, v135
	v_and_b32_e32 v63, s23, v135
	v_dot4c_i32_i8_e32 v64, v56, v34
	v_dot4c_i32_i8_e32 v86, v57, v35
	v_dot4c_i32_i8_e32 v65, v58, v34
	v_dot4c_i32_i8_e32 v87, v59, v35
	v_dot4c_i32_i8_e32 v66, v60, v34
	v_dot4c_i32_i8_e32 v88, v61, v35
	v_dot4c_i32_i8_e32 v67, v62, v34
	v_dot4c_i32_i8_e32 v89, v63, v35
	v_and_b32_e32 v56, s21, v124
	v_and_b32_e32 v57, s23, v124
	v_and_b32_e32 v58, s21, v128
	v_and_b32_e32 v59, s23, v128
	v_and_b32_e32 v60, s21, v132
	v_and_b32_e32 v61, s23, v132
	v_and_b32_e32 v62, s21, v136
	v_and_b32_e32 v63, s23, v136
	v_dot4c_i32_i8_e32 v64, v56, v36
; __device__ __forceinline__ void phase_peer_u(const Params& p, int layer, int xs, int wid0, int wstride, char* smraw) {
;     ...
;     for (int i = 0; i < 16; ++i) {
;       int a = 0;
; #pragma unroll
;       for (int m = 0; m < 4; ++m) {
;         const unsigned dw = q[i][m];
;         a = __builtin_amdgcn_sdot4((int)(dw & 0x0f0f0f0fu), xq[2 * m], a, false);
;         a = __builtin_amdgcn_sdot4((int)((dw >> 4) & 0x0f0f0f0fu), xq[2 * m + 1], a, false);
;       }
;       a -= corr;
	v_dot4c_i32_i8_e32 v86, v57, v37
	v_dot4c_i32_i8_e32 v65, v58, v36
	v_dot4c_i32_i8_e32 v87, v59, v37
	v_dot4c_i32_i8_e32 v66, v60, v36
	v_dot4c_i32_i8_e32 v88, v61, v37
	v_dot4c_i32_i8_e32 v67, v62, v36
	v_dot4c_i32_i8_e32 v89, v63, v37
	v_and_b32_e32 v56, s21, v125
	v_and_b32_e32 v57, s23, v125
	v_and_b32_e32 v58, s21, v129
	v_and_b32_e32 v59, s23, v129
	v_and_b32_e32 v60, s21, v133
	v_and_b32_e32 v61, s23, v133
	v_and_b32_e32 v62, s21, v137
	v_and_b32_e32 v63, s23, v137
	v_dot4c_i32_i8_e32 v64, v56, v38
	v_dot4c_i32_i8_e32 v86, v57, v39
	v_dot4c_i32_i8_e32 v65, v58, v38
	v_dot4c_i32_i8_e32 v87, v59, v39
	v_dot4c_i32_i8_e32 v66, v60, v38
	v_dot4c_i32_i8_e32 v88, v61, v39
	v_dot4c_i32_i8_e32 v67, v62, v38
	v_dot4c_i32_i8_e32 v89, v63, v39
	s_nop 0
	v_lshl_add_u32 v72, v64, 4, v86
	v_lshl_add_u32 v73, v65, 4, v87
	v_lshl_add_u32 v74, v66, 4, v88
	v_lshl_add_u32 v75, v67, 4, v89
	v_and_b32_e32 v56, s21, v138
	v_and_b32_e32 v57, s23, v138
	v_and_b32_e32 v58, s21, v142
	v_and_b32_e32 v59, s23, v142
	v_and_b32_e32 v60, s21, v146
	v_and_b32_e32 v61, s23, v146
	v_and_b32_e32 v62, s21, v150
	v_and_b32_e32 v63, s23, v150
	v_dot4_i32_i8 v64, v56, v32, v85
	v_dot4_i32_i8 v86, v57, v33, 0
	v_dot4_i32_i8 v65, v58, v32, v85
	v_dot4_i32_i8 v87, v59, v33, 0
	v_dot4_i32_i8 v66, v60, v32, v85
	v_dot4_i32_i8 v88, v61, v33, 0
	v_dot4_i32_i8 v67, v62, v32, v85
	v_dot4_i32_i8 v89, v63, v33, 0
	v_and_b32_e32 v56, s21, v139
	v_and_b32_e32 v57, s23, v139
	v_and_b32_e32 v58, s21, v143
	v_and_b32_e32 v59, s23, v143
	v_and_b32_e32 v60, s21, v147
	v_and_b32_e32 v61, s23, v147
	v_and_b32_e32 v62, s21, v151
	v_and_b32_e32 v63, s23, v151
	v_dot4c_i32_i8_e32 v64, v56, v34
	v_dot4c_i32_i8_e32 v86, v57, v35
	v_dot4c_i32_i8_e32 v65, v58, v34
	v_dot4c_i32_i8_e32 v87, v59, v35
	v_dot4c_i32_i8_e32 v66, v60, v34
	v_dot4c_i32_i8_e32 v88, v61, v35
	v_dot4c_i32_i8_e32 v67, v62, v34
	v_dot4c_i32_i8_e32 v89, v63, v35
	v_and_b32_e32 v56, s21, v140
	v_and_b32_e32 v57, s23, v140
	v_and_b32_e32 v58, s21, v144
	v_and_b32_e32 v59, s23, v144
	v_and_b32_e32 v60, s21, v148
	v_and_b32_e32 v61, s23, v148
	v_and_b32_e32 v62, s21, v152
	v_and_b32_e32 v63, s23, v152
	v_dot4c_i32_i8_e32 v64, v56, v36
	v_dot4c_i32_i8_e32 v86, v57, v37
	v_dot4c_i32_i8_e32 v65, v58, v36
	v_dot4c_i32_i8_e32 v87, v59, v37
	v_dot4c_i32_i8_e32 v66, v60, v36
	v_dot4c_i32_i8_e32 v88, v61, v37
	v_dot4c_i32_i8_e32 v67, v62, v36
	v_dot4c_i32_i8_e32 v89, v63, v37
	v_and_b32_e32 v56, s21, v141
	v_and_b32_e32 v57, s23, v141
	v_and_b32_e32 v58, s21, v145
	v_and_b32_e32 v59, s23, v145
	v_and_b32_e32 v60, s21, v149
	v_and_b32_e32 v61, s23, v149
	v_and_b32_e32 v62, s21, v153
	v_and_b32_e32 v63, s23, v153
	v_dot4c_i32_i8_e32 v64, v56, v38
	v_dot4c_i32_i8_e32 v86, v57, v39
	v_dot4c_i32_i8_e32 v65, v58, v38
	v_dot4c_i32_i8_e32 v87, v59, v39
	v_dot4c_i32_i8_e32 v66, v60, v38
	v_dot4c_i32_i8_e32 v88, v61, v39
	v_dot4c_i32_i8_e32 v67, v62, v38
	v_dot4c_i32_i8_e32 v89, v63, v39
	s_nop 0
	v_lshl_add_u32 v76, v64, 4, v86
	v_lshl_add_u32 v77, v65, 4, v87
	v_lshl_add_u32 v78, v66, 4, v88
	v_lshl_add_u32 v79, v67, 4, v89
	v_and_b32_e32 v56, s21, v154
	v_and_b32_e32 v57, s23, v154
	v_and_b32_e32 v58, s21, v158
	v_and_b32_e32 v59, s23, v158
	v_and_b32_e32 v60, s21, v162
	v_and_b32_e32 v61, s23, v162
	v_and_b32_e32 v62, s21, v166
	v_and_b32_e32 v63, s23, v166
	v_dot4_i32_i8 v64, v56, v32, v85
	v_dot4_i32_i8 v86, v57, v33, 0
	v_dot4_i32_i8 v65, v58, v32, v85
	v_dot4_i32_i8 v87, v59, v33, 0
	v_dot4_i32_i8 v66, v60, v32, v85
	v_dot4_i32_i8 v88, v61, v33, 0
	v_dot4_i32_i8 v67, v62, v32, v85
	v_dot4_i32_i8 v89, v63, v33, 0
	v_and_b32_e32 v56, s21, v155
	v_and_b32_e32 v57, s23, v155
	v_and_b32_e32 v58, s21, v159
	v_and_b32_e32 v59, s23, v159
	v_and_b32_e32 v60, s21, v163
	v_and_b32_e32 v61, s23, v163
	v_and_b32_e32 v62, s21, v167
	v_and_b32_e32 v63, s23, v167
	v_dot4c_i32_i8_e32 v64, v56, v34
	v_dot4c_i32_i8_e32 v86, v57, v35
	v_dot4c_i32_i8_e32 v65, v58, v34
	v_dot4c_i32_i8_e32 v87, v59, v35
	v_dot4c_i32_i8_e32 v66, v60, v34
	v_dot4c_i32_i8_e32 v88, v61, v35
	v_dot4c_i32_i8_e32 v67, v62, v34
; __device__ __forceinline__ void phase_peer_u(const Params& p, int layer, int xs, int wid0, int wstride, char* smraw) {
;     ...
;     for (int i = 0; i < 16; ++i) {
;       int a = 0;
; #pragma unroll
;       for (int m = 0; m < 4; ++m) {
;         const unsigned dw = q[i][m];
;         a = __builtin_amdgcn_sdot4((int)(dw & 0x0f0f0f0fu), xq[2 * m], a, false);
;         a = __builtin_amdgcn_sdot4((int)((dw >> 4) & 0x0f0f0f0fu), xq[2 * m + 1], a, false);
;       }
;       a -= corr;
;       a += __builtin_amdgcn_update_dpp(0, a, 0xB1, 0xF, 0xF, true);
;       a += __builtin_amdgcn_update_dpp(0, a, 0x4E, 0xF, 0xF, true);
;       a += __builtin_amdgcn_update_dpp(0, a, 0x141, 0xF, 0xF, true);
;       pr[i] = (float)a * sx;
;     }
;     if (j == 0) {
;       f32x4* dst = (f32x4*)((char*)p.actp + ((unsigned)t * 4096u + (unsigned)(sl * 512 + g * 64)));
; #pragma unroll
;       for (int q4 = 0; q4 < 4; ++q4) dst[q4] = f32x4{pr[q4 * 4], pr[q4 * 4 + 1], pr[q4 * 4 + 2], pr[q4 * 4 + 3]};
;     }
	v_dot4c_i32_i8_e32 v89, v63, v35
	v_and_b32_e32 v56, s21, v156
	v_and_b32_e32 v57, s23, v156
	v_and_b32_e32 v58, s21, v160
	v_and_b32_e32 v59, s23, v160
	v_and_b32_e32 v60, s21, v164
	v_and_b32_e32 v61, s23, v164
	v_and_b32_e32 v62, s21, v168
	v_and_b32_e32 v63, s23, v168
	v_dot4c_i32_i8_e32 v64, v56, v36
	v_dot4c_i32_i8_e32 v86, v57, v37
	v_dot4c_i32_i8_e32 v65, v58, v36
	v_dot4c_i32_i8_e32 v87, v59, v37
	v_dot4c_i32_i8_e32 v66, v60, v36
	v_dot4c_i32_i8_e32 v88, v61, v37
	v_dot4c_i32_i8_e32 v67, v62, v36
	v_dot4c_i32_i8_e32 v89, v63, v37
	v_and_b32_e32 v56, s21, v157
	v_and_b32_e32 v57, s23, v157
	v_and_b32_e32 v58, s21, v161
	v_and_b32_e32 v59, s23, v161
	v_and_b32_e32 v60, s21, v165
	v_and_b32_e32 v61, s23, v165
	v_and_b32_e32 v62, s21, v169
	v_and_b32_e32 v63, s23, v169
	v_dot4c_i32_i8_e32 v64, v56, v38
	v_dot4c_i32_i8_e32 v86, v57, v39
	v_dot4c_i32_i8_e32 v65, v58, v38
	v_dot4c_i32_i8_e32 v87, v59, v39
	v_dot4c_i32_i8_e32 v66, v60, v38
	v_dot4c_i32_i8_e32 v88, v61, v39
	v_dot4c_i32_i8_e32 v67, v62, v38
	v_dot4c_i32_i8_e32 v89, v63, v39
	s_nop 0
	v_lshl_add_u32 v80, v64, 4, v86
	v_lshl_add_u32 v81, v65, 4, v87
	v_lshl_add_u32 v82, v66, 4, v88
	v_lshl_add_u32 v83, v67, 4, v89
	v_cndmask_b32_e64 v94, v76, v68, s[12:13]
	v_cndmask_b32_e64 v95, v77, v69, s[12:13]
	v_cndmask_b32_e64 v96, v78, v70, s[12:13]
	v_cndmask_b32_e64 v97, v79, v71, s[12:13]
	v_cndmask_b32_e64 v98, v80, v72, s[12:13]
	v_cndmask_b32_e64 v99, v81, v73, s[12:13]
	v_cndmask_b32_e64 v100, v82, v74, s[12:13]
	v_cndmask_b32_e64 v101, v83, v75, s[12:13]
	v_cndmask_b32_e64 v86, v68, v76, s[12:13]
	v_cndmask_b32_e64 v87, v69, v77, s[12:13]
	v_cndmask_b32_e64 v88, v70, v78, s[12:13]
	v_cndmask_b32_e64 v89, v71, v79, s[12:13]
	v_cndmask_b32_e64 v90, v72, v80, s[12:13]
	v_cndmask_b32_e64 v91, v73, v81, s[12:13]
	v_cndmask_b32_e64 v92, v74, v82, s[12:13]
	v_cndmask_b32_e64 v93, v75, v83, s[12:13]
	v_add_u32_dpp v68, v94, v86 row_half_mirror row_mask:0xf bank_mask:0xf bound_ctrl:1
	v_add_u32_dpp v69, v95, v87 row_half_mirror row_mask:0xf bank_mask:0xf bound_ctrl:1
	v_add_u32_dpp v70, v96, v88 row_half_mirror row_mask:0xf bank_mask:0xf bound_ctrl:1
	v_add_u32_dpp v71, v97, v89 row_half_mirror row_mask:0xf bank_mask:0xf bound_ctrl:1
	v_add_u32_dpp v72, v98, v90 row_half_mirror row_mask:0xf bank_mask:0xf bound_ctrl:1
	v_add_u32_dpp v73, v99, v91 row_half_mirror row_mask:0xf bank_mask:0xf bound_ctrl:1
	v_add_u32_dpp v74, v100, v92 row_half_mirror row_mask:0xf bank_mask:0xf bound_ctrl:1
	v_add_u32_dpp v75, v101, v93 row_half_mirror row_mask:0xf bank_mask:0xf bound_ctrl:1
	v_cndmask_b32_e64 v94, v70, v68, s[72:73]
	v_cndmask_b32_e64 v95, v71, v69, s[72:73]
	v_cndmask_b32_e64 v96, v74, v72, s[72:73]
	v_cndmask_b32_e64 v97, v75, v73, s[72:73]
	v_cndmask_b32_e64 v86, v68, v70, s[72:73]
	v_cndmask_b32_e64 v87, v69, v71, s[72:73]
	v_cndmask_b32_e64 v88, v72, v74, s[72:73]
	v_cndmask_b32_e64 v89, v73, v75, s[72:73]
	v_add_u32_dpp v68, v94, v86 quad_perm:[1,0,3,2] row_mask:0xf bank_mask:0xf bound_ctrl:1
	v_add_u32_dpp v69, v95, v87 quad_perm:[1,0,3,2] row_mask:0xf bank_mask:0xf bound_ctrl:1
	v_add_u32_dpp v70, v96, v88 quad_perm:[1,0,3,2] row_mask:0xf bank_mask:0xf bound_ctrl:1
	v_add_u32_dpp v71, v97, v89 quad_perm:[1,0,3,2] row_mask:0xf bank_mask:0xf bound_ctrl:1
	v_cndmask_b32_e64 v94, v70, v68, s[74:75]
	v_cndmask_b32_e64 v95, v71, v69, s[74:75]
	v_cndmask_b32_e64 v86, v68, v70, s[74:75]
	v_cndmask_b32_e64 v87, v69, v71, s[74:75]
	v_add_u32_dpp v68, v94, v86 quad_perm:[2,3,0,1] row_mask:0xf bank_mask:0xf bound_ctrl:1
	v_add_u32_dpp v69, v95, v87 quad_perm:[2,3,0,1] row_mask:0xf bank_mask:0xf bound_ctrl:1
	v_ashrrev_i32_e32 v68, 4, v68
	v_ashrrev_i32_e32 v69, 4, v69
	v_cvt_f32_i32_e32 v68, v68
	v_cvt_f32_i32_e32 v69, v69
	s_lshl_b32 s70, s60, 1
	s_add_u32 s70, s70, s28
	s_lshl_b32 s70, s70, 12
	s_add_u32 s70, s70, s68
	v_pk_mul_f32 v[68:69], v[52:53], v[68:69] op_sel_hi:[0,1]
	v_add_u32_e32 v9, s70, v0
	global_store_dwordx2 v9, v[68:69], s[64:65]
	s_mov_b32 s60, s62
	s_cmp_lt_u32 s60, s61
	s_cbranch_scc0 .Lmy_pu0_done

; __device__ __forceinline__ float bflo(unsigned u) { return __uint_as_float(u << 16); }
; __device__ __forceinline__ float bfhi(unsigned u) { return __uint_as_float(u & 0xffff0000u); }
; __device__ __forceinline__ void phase_peer_u(const Params& p, int layer, int xs, int wid0, int wstride, char* smraw) {
;     ...
;       const float x0 = bflo(xv[0]), x1 = bfhi(xv[0]), x2 = bflo(xv[1]), x3 = bfhi(xv[1]);
;       float mx = fmaxf(fmaxf(fabsf(x0), fabsf(x1)), fmaxf(fabsf(x2), fabsf(x3)));
; #pragma unroll
;       for (int m = 32; m >= 1; m >>= 1) mx = fmaxf(mx, __shfl_xor(mx, m));
;       const float inv = mx > 0.f ? 127.f / mx : 0.f;
;       sx = mx * (1.f / 127.f);
;       const int q0 = __float2int_rn(x0 * inv), q1 = __float2int_rn(x1 * inv), q2 = __float2int_rn(x2 * inv), q3 = __float2int_rn(x3 * inv);
;       asm volatile("" ::: "memory");
;       *(int*)(xqs + l * 4) = (q0 & 0xff) | ((q1 & 0xff) << 8) | ((q2 & 0xff) << 16) | ((q3 & 0xff) << 24);
;       asm volatile("" ::: "memory");
;       __builtin_amdgcn_wave_barrier();
;       asm volatile("" ::: "memory");
;       const u32x4 xa = *(const u32x4*)(xqs + j * 32), xb = *(const u32x4*)(xqs + j * 32 + 16);
;       asm volatile("" ::: "memory");
; #pragma unroll
;       for (int m = 0; m < 4; ++m) { xq[m] = (int)xa[m]; xq[4 + m] = (int)xb[m]; }
; #pragma unroll
;       for (int m = 0; m < 8; ++m) sumx = __builtin_amdgcn_sdot4(xq[m], 0x01010101, sumx, false);
;     }
;     const int corr = 8 * sumx;
;     float pr[16];
; #pragma unroll
;     for (int i = 0; i < 16; ++i) {
;       int a = 0;
; #pragma unroll
;       for (int m = 0; m < 4; ++m) {
;         const unsigned dw = q[i][m];
;         a = __builtin_amdgcn_sdot4((int)(dw & 0x0f0f0f0fu), xq[2 * m], a, false);
;         a = __builtin_amdgcn_sdot4((int)((dw >> 4) & 0x0f0f0f0fu), xq[2 * m + 1], a, false);
;       }
;       a -= corr;
.Lmy_pu0_noissueB:
	v_lshlrev_b32_e32 v40, 16, v28
	v_and_b32_e32 v41, 0xffff0000, v28
	v_lshlrev_b32_e32 v42, 16, v29
	v_and_b32_e32 v43, 0xffff0000, v29
	v_max_f32_e64 v44, |v40|, |v41|
	v_max3_f32 v44, |v42|, |v43|, v44
	s_nop 1
	v_max_f32_dpp v44, v44, v44 quad_perm:[1,0,3,2] row_mask:0xf bank_mask:0xf bound_ctrl:1
	s_nop 1
	v_max_f32_dpp v44, v44, v44 quad_perm:[2,3,0,1] row_mask:0xf bank_mask:0xf bound_ctrl:1
	s_nop 1
	v_max_f32_dpp v44, v44, v44 row_half_mirror row_mask:0xf bank_mask:0xf bound_ctrl:1
	s_nop 1
	v_max_f32_dpp v44, v44, v44 row_mirror row_mask:0xf bank_mask:0xf bound_ctrl:1
	s_nop 0
	v_readlane_b32 s6, v44, 0
	v_readlane_b32 s7, v44, 16
	v_readlane_b32 s10, v44, 32
	v_readlane_b32 s11, v44, 48
	s_nop 1
	v_mov_b32_e32 v45, s6
	v_max_f32_e32 v45, s7, v45
	v_max_f32_e32 v45, s10, v45
	v_max_f32_e32 v45, s11, v45
	v_div_scale_f32 v46, s[18:19], v45, v45, s69
	v_rcp_f32_e32 v47, v46
	s_nop 0
	v_fma_f32 v48, -v46, v47, 1.0
	v_fmac_f32_e32 v47, v48, v47
	v_div_scale_f32 v48, vcc, s69, v45, s69
	v_mul_f32_e32 v49, v48, v47
	v_fma_f32 v50, -v46, v49, v48
	v_fmac_f32_e32 v49, v50, v47
	v_fma_f32 v46, -v46, v49, v48
	v_div_fmas_f32 v46, v46, v47, v49
	v_div_fixup_f32 v46, v46, v45, s69
	v_cmp_lt_f32_e32 vcc, 0, v45
	v_mul_f32_e32 v52, 0x3c010204, v45
	v_mov_b32_e32 v84, 0
	v_cndmask_b32_e32 v46, 0, v46, vcc
	v_mul_f32_e32 v40, v46, v40
	v_mul_f32_e32 v41, v46, v41
	v_mul_f32_e32 v42, v46, v42
	v_mul_f32_e32 v43, v46, v43
	v_rndne_f32_e32 v40, v40
	v_rndne_f32_e32 v41, v41
	v_rndne_f32_e32 v42, v42
	v_rndne_f32_e32 v43, v43
	v_cvt_i32_f32_e32 v40, v40
	v_cvt_i32_f32_e32 v41, v41
	v_cvt_i32_f32_e32 v42, v42
	v_cvt_i32_f32_e32 v43, v43
	v_and_b32_e32 v40, 0xff, v40
	v_and_b32_e32 v41, 0xff, v41
	v_and_b32_e32 v42, 0xff, v42
	v_lshl_or_b32 v40, v41, 8, v40
	v_lshl_or_b32 v40, v42, 16, v40
	v_lshl_or_b32 v40, v43, 24, v40
	ds_write_b32 v3, v40
	ds_read_b128 v[32:35], v4
	ds_read_b128 v[36:39], v4 offset:16
	s_waitcnt lgkmcnt(0)
	v_dot4c_i32_i8_e32 v84, 0x1010101, v32
	v_dot4c_i32_i8_e32 v84, 0x1010101, v34
	v_dot4c_i32_i8_e32 v84, 0x1010101, v36
	v_dot4c_i32_i8_e32 v84, 0x1010101, v38
	v_and_b32_e32 v56, s21, v170
	v_and_b32_e32 v57, s23, v170
	v_and_b32_e32 v58, s21, v174
	v_and_b32_e32 v59, s23, v174
	v_and_b32_e32 v60, s21, v178
	v_and_b32_e32 v61, s23, v178
	v_and_b32_e32 v62, s21, v182
	v_and_b32_e32 v63, s23, v182
	v_mul_i32_i24_e32 v85, -8, v84
	v_dot4_i32_i8 v64, v56, v32, v85
	v_dot4_i32_i8 v86, v57, v33, 0
	v_dot4_i32_i8 v65, v58, v32, v85
	v_dot4_i32_i8 v87, v59, v33, 0
	v_dot4_i32_i8 v66, v60, v32, v85
	v_dot4_i32_i8 v88, v61, v33, 0
	v_dot4_i32_i8 v67, v62, v32, v85
	v_dot4_i32_i8 v89, v63, v33, 0
	v_and_b32_e32 v56, s21, v171
	v_and_b32_e32 v57, s23, v171
	v_and_b32_e32 v58, s21, v175
	v_and_b32_e32 v59, s23, v175
	v_and_b32_e32 v60, s21, v179
	v_and_b32_e32 v61, s23, v179
	v_and_b32_e32 v62, s21, v183
	v_and_b32_e32 v63, s23, v183
	v_dot4c_i32_i8_e32 v64, v56, v34
	v_dot4c_i32_i8_e32 v86, v57, v35
	v_dot4c_i32_i8_e32 v65, v58, v34
	v_dot4c_i32_i8_e32 v87, v59, v35
	v_dot4c_i32_i8_e32 v66, v60, v34
	v_dot4c_i32_i8_e32 v88, v61, v35
	v_dot4c_i32_i8_e32 v67, v62, v34
	v_dot4c_i32_i8_e32 v89, v63, v35
	v_and_b32_e32 v56, s21, v172
	v_and_b32_e32 v57, s23, v172
	v_and_b32_e32 v58, s21, v176
	v_and_b32_e32 v59, s23, v176
	v_and_b32_e32 v60, s21, v180
	v_and_b32_e32 v61, s23, v180
	v_and_b32_e32 v62, s21, v184
	v_and_b32_e32 v63, s23, v184
	v_dot4c_i32_i8_e32 v64, v56, v36
	v_dot4c_i32_i8_e32 v86, v57, v37
	v_dot4c_i32_i8_e32 v65, v58, v36
	v_dot4c_i32_i8_e32 v87, v59, v37
	v_dot4c_i32_i8_e32 v66, v60, v36
	v_dot4c_i32_i8_e32 v88, v61, v37
	v_dot4c_i32_i8_e32 v67, v62, v36
	v_dot4c_i32_i8_e32 v89, v63, v37
	v_and_b32_e32 v56, s21, v173
	v_and_b32_e32 v57, s23, v173
	v_and_b32_e32 v58, s21, v177
	v_and_b32_e32 v59, s23, v177
	v_and_b32_e32 v60, s21, v181
	v_and_b32_e32 v61, s23, v181
	v_and_b32_e32 v62, s21, v185
	v_and_b32_e32 v63, s23, v185
	v_dot4c_i32_i8_e32 v64, v56, v38
	v_dot4c_i32_i8_e32 v86, v57, v39
	v_dot4c_i32_i8_e32 v65, v58, v38
	v_dot4c_i32_i8_e32 v87, v59, v39
	v_dot4c_i32_i8_e32 v66, v60, v38
	v_dot4c_i32_i8_e32 v88, v61, v39
	v_dot4c_i32_i8_e32 v67, v62, v38
	v_dot4c_i32_i8_e32 v89, v63, v39
	s_nop 0
	v_lshl_add_u32 v68, v64, 4, v86
	v_lshl_add_u32 v69, v65, 4, v87
	v_lshl_add_u32 v70, v66, 4, v88
	v_lshl_add_u32 v71, v67, 4, v89
	v_and_b32_e32 v56, s21, v192
	v_and_b32_e32 v57, s23, v192
	v_and_b32_e32 v58, s21, v196
	v_and_b32_e32 v59, s23, v196
	v_and_b32_e32 v60, s21, v200
	v_and_b32_e32 v61, s23, v200
	v_and_b32_e32 v62, s21, v204
	v_and_b32_e32 v63, s23, v204
	v_dot4_i32_i8 v64, v56, v32, v85
	v_dot4_i32_i8 v86, v57, v33, 0
	v_dot4_i32_i8 v65, v58, v32, v85
	v_dot4_i32_i8 v87, v59, v33, 0
	v_dot4_i32_i8 v66, v60, v32, v85
	v_dot4_i32_i8 v88, v61, v33, 0
	v_dot4_i32_i8 v67, v62, v32, v85
	v_dot4_i32_i8 v89, v63, v33, 0
	v_and_b32_e32 v56, s21, v193
	v_and_b32_e32 v57, s23, v193
	v_and_b32_e32 v58, s21, v197
	v_and_b32_e32 v59, s23, v197
	v_and_b32_e32 v60, s21, v201
	v_and_b32_e32 v61, s23, v201
	v_and_b32_e32 v62, s21, v205
	v_and_b32_e32 v63, s23, v205
	v_dot4c_i32_i8_e32 v64, v56, v34
	v_dot4c_i32_i8_e32 v86, v57, v35
	v_dot4c_i32_i8_e32 v65, v58, v34
	v_dot4c_i32_i8_e32 v87, v59, v35
	v_dot4c_i32_i8_e32 v66, v60, v34
	v_dot4c_i32_i8_e32 v88, v61, v35
	v_dot4c_i32_i8_e32 v67, v62, v34
	v_dot4c_i32_i8_e32 v89, v63, v35
	v_and_b32_e32 v56, s21, v194
	v_and_b32_e32 v57, s23, v194
	v_and_b32_e32 v58, s21, v198
	v_and_b32_e32 v59, s23, v198
	v_and_b32_e32 v60, s21, v202
	v_and_b32_e32 v61, s23, v202
	v_and_b32_e32 v62, s21, v206
	v_and_b32_e32 v63, s23, v206
	v_dot4c_i32_i8_e32 v64, v56, v36
; __device__ __forceinline__ void phase_peer_u(const Params& p, int layer, int xs, int wid0, int wstride, char* smraw) {
;     ...
;     for (int i = 0; i < 16; ++i) {
;       int a = 0;
; #pragma unroll
;       for (int m = 0; m < 4; ++m) {
;         const unsigned dw = q[i][m];
;         a = __builtin_amdgcn_sdot4((int)(dw & 0x0f0f0f0fu), xq[2 * m], a, false);
;         a = __builtin_amdgcn_sdot4((int)((dw >> 4) & 0x0f0f0f0fu), xq[2 * m + 1], a, false);
;       }
;       a -= corr;
	v_dot4c_i32_i8_e32 v86, v57, v37
	v_dot4c_i32_i8_e32 v65, v58, v36
	v_dot4c_i32_i8_e32 v87, v59, v37
	v_dot4c_i32_i8_e32 v66, v60, v36
	v_dot4c_i32_i8_e32 v88, v61, v37
	v_dot4c_i32_i8_e32 v67, v62, v36
	v_dot4c_i32_i8_e32 v89, v63, v37
	v_and_b32_e32 v56, s21, v195
	v_and_b32_e32 v57, s23, v195
	v_and_b32_e32 v58, s21, v199
	v_and_b32_e32 v59, s23, v199
	v_and_b32_e32 v60, s21, v203
	v_and_b32_e32 v61, s23, v203
	v_and_b32_e32 v62, s21, v207
	v_and_b32_e32 v63, s23, v207
	v_dot4c_i32_i8_e32 v64, v56, v38
	v_dot4c_i32_i8_e32 v86, v57, v39
	v_dot4c_i32_i8_e32 v65, v58, v38
	v_dot4c_i32_i8_e32 v87, v59, v39
	v_dot4c_i32_i8_e32 v66, v60, v38
	v_dot4c_i32_i8_e32 v88, v61, v39
	v_dot4c_i32_i8_e32 v67, v62, v38
	v_dot4c_i32_i8_e32 v89, v63, v39
	s_nop 0
	v_lshl_add_u32 v72, v64, 4, v86
	v_lshl_add_u32 v73, v65, 4, v87
	v_lshl_add_u32 v74, v66, 4, v88
	v_lshl_add_u32 v75, v67, 4, v89
	v_and_b32_e32 v56, s21, v208
	v_and_b32_e32 v57, s23, v208
	v_and_b32_e32 v58, s21, v212
	v_and_b32_e32 v59, s23, v212
	v_and_b32_e32 v60, s21, v216
	v_and_b32_e32 v61, s23, v216
	v_and_b32_e32 v62, s21, v220
	v_and_b32_e32 v63, s23, v220
	v_dot4_i32_i8 v64, v56, v32, v85
	v_dot4_i32_i8 v86, v57, v33, 0
	v_dot4_i32_i8 v65, v58, v32, v85
	v_dot4_i32_i8 v87, v59, v33, 0
	v_dot4_i32_i8 v66, v60, v32, v85
	v_dot4_i32_i8 v88, v61, v33, 0
	v_dot4_i32_i8 v67, v62, v32, v85
	v_dot4_i32_i8 v89, v63, v33, 0
	v_and_b32_e32 v56, s21, v209
	v_and_b32_e32 v57, s23, v209
	v_and_b32_e32 v58, s21, v213
	v_and_b32_e32 v59, s23, v213
	v_and_b32_e32 v60, s21, v217
	v_and_b32_e32 v61, s23, v217
	v_and_b32_e32 v62, s21, v221
	v_and_b32_e32 v63, s23, v221
	v_dot4c_i32_i8_e32 v64, v56, v34
	v_dot4c_i32_i8_e32 v86, v57, v35
	v_dot4c_i32_i8_e32 v65, v58, v34
	v_dot4c_i32_i8_e32 v87, v59, v35
	v_dot4c_i32_i8_e32 v66, v60, v34
	v_dot4c_i32_i8_e32 v88, v61, v35
	v_dot4c_i32_i8_e32 v67, v62, v34
	v_dot4c_i32_i8_e32 v89, v63, v35
	v_and_b32_e32 v56, s21, v210
	v_and_b32_e32 v57, s23, v210
	v_and_b32_e32 v58, s21, v214
	v_and_b32_e32 v59, s23, v214
	v_and_b32_e32 v60, s21, v218
	v_and_b32_e32 v61, s23, v218
	v_and_b32_e32 v62, s21, v222
	v_and_b32_e32 v63, s23, v222
	v_dot4c_i32_i8_e32 v64, v56, v36
	v_dot4c_i32_i8_e32 v86, v57, v37
	v_dot4c_i32_i8_e32 v65, v58, v36
	v_dot4c_i32_i8_e32 v87, v59, v37
	v_dot4c_i32_i8_e32 v66, v60, v36
	v_dot4c_i32_i8_e32 v88, v61, v37
	v_dot4c_i32_i8_e32 v67, v62, v36
	v_dot4c_i32_i8_e32 v89, v63, v37
	v_and_b32_e32 v56, s21, v211
	v_and_b32_e32 v57, s23, v211
	v_and_b32_e32 v58, s21, v215
	v_and_b32_e32 v59, s23, v215
	v_and_b32_e32 v60, s21, v219
	v_and_b32_e32 v61, s23, v219
	v_and_b32_e32 v62, s21, v223
	v_and_b32_e32 v63, s23, v223
	v_dot4c_i32_i8_e32 v64, v56, v38
	v_dot4c_i32_i8_e32 v86, v57, v39
	v_dot4c_i32_i8_e32 v65, v58, v38
	v_dot4c_i32_i8_e32 v87, v59, v39
	v_dot4c_i32_i8_e32 v66, v60, v38
	v_dot4c_i32_i8_e32 v88, v61, v39
	v_dot4c_i32_i8_e32 v67, v62, v38
	v_dot4c_i32_i8_e32 v89, v63, v39
	s_nop 0
	v_lshl_add_u32 v76, v64, 4, v86
	v_lshl_add_u32 v77, v65, 4, v87
	v_lshl_add_u32 v78, v66, 4, v88
	v_lshl_add_u32 v79, v67, 4, v89
	v_and_b32_e32 v56, s21, v224
	v_and_b32_e32 v57, s23, v224
	v_and_b32_e32 v58, s21, v228
	v_and_b32_e32 v59, s23, v228
	v_and_b32_e32 v60, s21, v232
	v_and_b32_e32 v61, s23, v232
	v_and_b32_e32 v62, s21, v236
	v_and_b32_e32 v63, s23, v236
	v_dot4_i32_i8 v64, v56, v32, v85
	v_dot4_i32_i8 v86, v57, v33, 0
	v_dot4_i32_i8 v65, v58, v32, v85
	v_dot4_i32_i8 v87, v59, v33, 0
	v_dot4_i32_i8 v66, v60, v32, v85
	v_dot4_i32_i8 v88, v61, v33, 0
	v_dot4_i32_i8 v67, v62, v32, v85
	v_dot4_i32_i8 v89, v63, v33, 0
	v_and_b32_e32 v56, s21, v225
	v_and_b32_e32 v57, s23, v225
	v_and_b32_e32 v58, s21, v229
	v_and_b32_e32 v59, s23, v229
	v_and_b32_e32 v60, s21, v233
	v_and_b32_e32 v61, s23, v233
	v_and_b32_e32 v62, s21, v237
	v_and_b32_e32 v63, s23, v237
	v_dot4c_i32_i8_e32 v64, v56, v34
	v_dot4c_i32_i8_e32 v86, v57, v35
	v_dot4c_i32_i8_e32 v65, v58, v34
	v_dot4c_i32_i8_e32 v87, v59, v35
	v_dot4c_i32_i8_e32 v66, v60, v34
	v_dot4c_i32_i8_e32 v88, v61, v35
	v_dot4c_i32_i8_e32 v67, v62, v34
; __device__ __forceinline__ void phase_peer_u(const Params& p, int layer, int xs, int wid0, int wstride, char* smraw) {
;     ...
;     for (int i = 0; i < 16; ++i) {
;       int a = 0;
; #pragma unroll
;       for (int m = 0; m < 4; ++m) {
;         const unsigned dw = q[i][m];
;         a = __builtin_amdgcn_sdot4((int)(dw & 0x0f0f0f0fu), xq[2 * m], a, false);
;         a = __builtin_amdgcn_sdot4((int)((dw >> 4) & 0x0f0f0f0fu), xq[2 * m + 1], a, false);
;       }
;       a -= corr;
;       a += __builtin_amdgcn_update_dpp(0, a, 0xB1, 0xF, 0xF, true);
;       a += __builtin_amdgcn_update_dpp(0, a, 0x4E, 0xF, 0xF, true);
;       a += __builtin_amdgcn_update_dpp(0, a, 0x141, 0xF, 0xF, true);
;       pr[i] = (float)a * sx;
;     }
;     if (j == 0) {
;       f32x4* dst = (f32x4*)((char*)p.actp + ((unsigned)t * 4096u + (unsigned)(sl * 512 + g * 64)));
; #pragma unroll
;       for (int q4 = 0; q4 < 4; ++q4) dst[q4] = f32x4{pr[q4 * 4], pr[q4 * 4 + 1], pr[q4 * 4 + 2], pr[q4 * 4 + 3]};
;     }
	v_dot4c_i32_i8_e32 v89, v63, v35
	v_and_b32_e32 v56, s21, v226
	v_and_b32_e32 v57, s23, v226
	v_and_b32_e32 v58, s21, v230
	v_and_b32_e32 v59, s23, v230
	v_and_b32_e32 v60, s21, v234
	v_and_b32_e32 v61, s23, v234
	v_and_b32_e32 v62, s21, v238
	v_and_b32_e32 v63, s23, v238
	v_dot4c_i32_i8_e32 v64, v56, v36
	v_dot4c_i32_i8_e32 v86, v57, v37
	v_dot4c_i32_i8_e32 v65, v58, v36
	v_dot4c_i32_i8_e32 v87, v59, v37
	v_dot4c_i32_i8_e32 v66, v60, v36
	v_dot4c_i32_i8_e32 v88, v61, v37
	v_dot4c_i32_i8_e32 v67, v62, v36
	v_dot4c_i32_i8_e32 v89, v63, v37
	v_and_b32_e32 v56, s21, v227
	v_and_b32_e32 v57, s23, v227
	v_and_b32_e32 v58, s21, v231
	v_and_b32_e32 v59, s23, v231
	v_and_b32_e32 v60, s21, v235
	v_and_b32_e32 v61, s23, v235
	v_and_b32_e32 v62, s21, v239
	v_and_b32_e32 v63, s23, v239
	v_dot4c_i32_i8_e32 v64, v56, v38
	v_dot4c_i32_i8_e32 v86, v57, v39
	v_dot4c_i32_i8_e32 v65, v58, v38
	v_dot4c_i32_i8_e32 v87, v59, v39
	v_dot4c_i32_i8_e32 v66, v60, v38
	v_dot4c_i32_i8_e32 v88, v61, v39
	v_dot4c_i32_i8_e32 v67, v62, v38
	v_dot4c_i32_i8_e32 v89, v63, v39
	s_nop 0
	v_lshl_add_u32 v80, v64, 4, v86
	v_lshl_add_u32 v81, v65, 4, v87
	v_lshl_add_u32 v82, v66, 4, v88
	v_lshl_add_u32 v83, v67, 4, v89
	v_cndmask_b32_e64 v94, v76, v68, s[12:13]
	v_cndmask_b32_e64 v95, v77, v69, s[12:13]
	v_cndmask_b32_e64 v96, v78, v70, s[12:13]
	v_cndmask_b32_e64 v97, v79, v71, s[12:13]
	v_cndmask_b32_e64 v98, v80, v72, s[12:13]
	v_cndmask_b32_e64 v99, v81, v73, s[12:13]
	v_cndmask_b32_e64 v100, v82, v74, s[12:13]
	v_cndmask_b32_e64 v101, v83, v75, s[12:13]
	v_cndmask_b32_e64 v86, v68, v76, s[12:13]
	v_cndmask_b32_e64 v87, v69, v77, s[12:13]
	v_cndmask_b32_e64 v88, v70, v78, s[12:13]
	v_cndmask_b32_e64 v89, v71, v79, s[12:13]
	v_cndmask_b32_e64 v90, v72, v80, s[12:13]
	v_cndmask_b32_e64 v91, v73, v81, s[12:13]
	v_cndmask_b32_e64 v92, v74, v82, s[12:13]
	v_cndmask_b32_e64 v93, v75, v83, s[12:13]
	v_add_u32_dpp v68, v94, v86 row_half_mirror row_mask:0xf bank_mask:0xf bound_ctrl:1
	v_add_u32_dpp v69, v95, v87 row_half_mirror row_mask:0xf bank_mask:0xf bound_ctrl:1
	v_add_u32_dpp v70, v96, v88 row_half_mirror row_mask:0xf bank_mask:0xf bound_ctrl:1
	v_add_u32_dpp v71, v97, v89 row_half_mirror row_mask:0xf bank_mask:0xf bound_ctrl:1
	v_add_u32_dpp v72, v98, v90 row_half_mirror row_mask:0xf bank_mask:0xf bound_ctrl:1
	v_add_u32_dpp v73, v99, v91 row_half_mirror row_mask:0xf bank_mask:0xf bound_ctrl:1
	v_add_u32_dpp v74, v100, v92 row_half_mirror row_mask:0xf bank_mask:0xf bound_ctrl:1
	v_add_u32_dpp v75, v101, v93 row_half_mirror row_mask:0xf bank_mask:0xf bound_ctrl:1
	v_cndmask_b32_e64 v94, v70, v68, s[72:73]
	v_cndmask_b32_e64 v95, v71, v69, s[72:73]
	v_cndmask_b32_e64 v96, v74, v72, s[72:73]
	v_cndmask_b32_e64 v97, v75, v73, s[72:73]
	v_cndmask_b32_e64 v86, v68, v70, s[72:73]
	v_cndmask_b32_e64 v87, v69, v71, s[72:73]
	v_cndmask_b32_e64 v88, v72, v74, s[72:73]
	v_cndmask_b32_e64 v89, v73, v75, s[72:73]
	v_add_u32_dpp v68, v94, v86 quad_perm:[1,0,3,2] row_mask:0xf bank_mask:0xf bound_ctrl:1
	v_add_u32_dpp v69, v95, v87 quad_perm:[1,0,3,2] row_mask:0xf bank_mask:0xf bound_ctrl:1
	v_add_u32_dpp v70, v96, v88 quad_perm:[1,0,3,2] row_mask:0xf bank_mask:0xf bound_ctrl:1
	v_add_u32_dpp v71, v97, v89 quad_perm:[1,0,3,2] row_mask:0xf bank_mask:0xf bound_ctrl:1
	v_cndmask_b32_e64 v94, v70, v68, s[74:75]
	v_cndmask_b32_e64 v95, v71, v69, s[74:75]
	v_cndmask_b32_e64 v86, v68, v70, s[74:75]
	v_cndmask_b32_e64 v87, v69, v71, s[74:75]
	v_add_u32_dpp v68, v94, v86 quad_perm:[2,3,0,1] row_mask:0xf bank_mask:0xf bound_ctrl:1
	v_add_u32_dpp v69, v95, v87 quad_perm:[2,3,0,1] row_mask:0xf bank_mask:0xf bound_ctrl:1
	v_ashrrev_i32_e32 v68, 4, v68
	v_ashrrev_i32_e32 v69, 4, v69
	v_cvt_f32_i32_e32 v68, v68
	v_cvt_f32_i32_e32 v69, v69
	s_lshl_b32 s70, s60, 1
	s_add_u32 s70, s70, s28
	s_lshl_b32 s70, s70, 12
	s_add_u32 s70, s70, s68
	v_pk_mul_f32 v[68:69], v[52:53], v[68:69] op_sel_hi:[0,1]
	v_add_u32_e32 v9, s70, v0
	global_store_dwordx2 v9, v[68:69], s[64:65]
	s_mov_b32 s60, s62
	s_cmp_lt_u32 s60, s61
	s_cbranch_scc1 .Lmy_pu0_bodyA
